# WOUT phase: hand-written f32-residual epilogue (register ring, packed math, compact row-sum stores), row 0 fetched during the last K trip
# baseline (speedup 1.0000x reference)
.LBB0_428:
	ds_read_b128 v[128:131], v204
	ds_read_b128 v[132:135], v204 offset:1024
	ds_read_b128 v[136:139], v204 offset:2048
	ds_read_b128 v[140:143], v204 offset:3072
	ds_read_b128 v[144:147], v205
	ds_read_b128 v[148:151], v205 offset:1024
	ds_read_b128 v[152:155], v205 offset:2048
	ds_read_b128 v[156:159], v205 offset:3072
	s_add_u32 s36, s34, 0xfffc0080
	s_addc_u32 s37, s35, -1
	s_cmp_eq_u32 s55, 12
	s_cselect_b32 s39, s29, s37
	s_cselect_b32 s38, s28, s36
	s_cselect_b32 s37, s31, s19
	s_cselect_b32 s36, s30, s15
	v_lshl_add_u64 v[198:199], s[34:35], 0, v[184:185]
	s_add_i32 m0, s40, 0xc000
	ds_read_b128 v[160:163], v206
	ds_read_b128 v[164:167], v206 offset:1024
	ds_read_b128 v[168:171], v206 offset:2048
	ds_read_b128 v[172:175], v206 offset:3072
	ds_read_b128 v[190:193], v206 offset:4096
	ds_read_b128 v[194:197], v206 offset:5120
	ds_read_b128 v[208:211], v206 offset:6144
	ds_read_b128 v[212:215], v206 offset:7168
	global_load_lds_dwordx4 v[198:199], off
	v_lshl_add_u64 v[198:199], s[34:35], 0, v[186:187]
	s_add_i32 m0, s40, 0xe000
	s_nop 0
	global_load_lds_dwordx4 v[198:199], off
	s_waitcnt vmcnt(8)
	s_waitcnt lgkmcnt(0)
	s_barrier
	s_setprio 1
	s_waitcnt lgkmcnt(0)
	v_mfma_f32_16x16x32_bf16 v[124:127], v[128:131], v[160:163], v[124:127]
	v_mfma_f32_16x16x32_bf16 v[120:123], v[136:139], v[160:163], v[120:123]
	v_mfma_f32_16x16x32_bf16 v[108:111], v[128:131], v[168:171], v[108:111]
	v_mfma_f32_16x16x32_bf16 v[104:107], v[136:139], v[168:171], v[104:107]
	v_mfma_f32_16x16x32_bf16 v[92:95], v[128:131], v[190:193], v[92:95]
	v_mfma_f32_16x16x32_bf16 v[88:91], v[136:139], v[190:193], v[88:91]
	v_mfma_f32_16x16x32_bf16 v[76:79], v[128:131], v[208:211], v[76:79]
	v_mfma_f32_16x16x32_bf16 v[72:75], v[136:139], v[208:211], v[72:75]
	v_mfma_f32_16x16x32_bf16 v[124:127], v[132:135], v[164:167], v[124:127]
	v_mfma_f32_16x16x32_bf16 v[120:123], v[140:143], v[164:167], v[120:123]
	v_mfma_f32_16x16x32_bf16 v[108:111], v[132:135], v[172:175], v[108:111]
	v_mfma_f32_16x16x32_bf16 v[104:107], v[140:143], v[172:175], v[104:107]
	v_mfma_f32_16x16x32_bf16 v[92:95], v[132:135], v[194:197], v[92:95]
	v_mfma_f32_16x16x32_bf16 v[88:91], v[140:143], v[194:197], v[88:91]
	v_mfma_f32_16x16x32_bf16 v[76:79], v[132:135], v[212:215], v[76:79]
	v_mfma_f32_16x16x32_bf16 v[72:75], v[140:143], v[212:215], v[72:75]
	s_setprio 0
	s_setprio 1
	v_mfma_f32_16x16x32_bf16 v[116:119], v[144:147], v[160:163], v[116:119]
	v_mfma_f32_16x16x32_bf16 v[112:115], v[152:155], v[160:163], v[112:115]
	v_mfma_f32_16x16x32_bf16 v[100:103], v[144:147], v[168:171], v[100:103]
	v_mfma_f32_16x16x32_bf16 v[96:99], v[152:155], v[168:171], v[96:99]
	v_mfma_f32_16x16x32_bf16 v[84:87], v[144:147], v[190:193], v[84:87]
	v_mfma_f32_16x16x32_bf16 v[80:83], v[152:155], v[190:193], v[80:83]
	v_mfma_f32_16x16x32_bf16 v[68:71], v[144:147], v[208:211], v[68:71]
	v_mfma_f32_16x16x32_bf16 v[64:67], v[152:155], v[208:211], v[64:67]
	v_mfma_f32_16x16x32_bf16 v[116:119], v[148:151], v[164:167], v[116:119]
	v_mfma_f32_16x16x32_bf16 v[112:115], v[156:159], v[164:167], v[112:115]
	v_mfma_f32_16x16x32_bf16 v[100:103], v[148:151], v[172:175], v[100:103]
	v_mfma_f32_16x16x32_bf16 v[96:99], v[156:159], v[172:175], v[96:99]
	v_mfma_f32_16x16x32_bf16 v[84:87], v[148:151], v[194:197], v[84:87]
	v_mfma_f32_16x16x32_bf16 v[80:83], v[156:159], v[194:197], v[80:83]
	v_mfma_f32_16x16x32_bf16 v[68:71], v[148:151], v[212:215], v[68:71]
	v_mfma_f32_16x16x32_bf16 v[64:67], v[156:159], v[212:215], v[64:67]
	s_setprio 0
	s_barrier
	s_add_i32 s56, s51, s33
	v_lshl_add_u64 v[198:199], s[36:37], 0, v[178:179]
	s_mov_b32 m0, s56
	ds_read_b128 v[160:163], v206 offset:16384
	ds_read_b128 v[164:167], v206 offset:17408
	ds_read_b128 v[168:171], v206 offset:18432
	ds_read_b128 v[172:175], v206 offset:19456
	ds_read_b128 v[190:193], v206 offset:20480
	ds_read_b128 v[194:197], v206 offset:21504
	ds_read_b128 v[208:211], v206 offset:22528
	ds_read_b128 v[212:215], v206 offset:23552
	global_load_lds_dwordx4 v[198:199], off
	s_add_i32 m0, s56, 0x2000
	s_add_u32 s56, s36, 0x40000
	v_lshl_add_u64 v[216:217], s[36:37], 0, v[182:183]
	s_addc_u32 s57, s37, 0
	s_add_i32 s58, s52, s33
	global_load_lds_dwordx4 v[216:217], off
	v_lshl_add_u64 v[218:219], s[56:57], 0, v[178:179]
	s_mov_b32 m0, s58
	v_lshl_add_u64 v[220:221], s[38:39], 0, v[180:181]
	global_load_lds_dwordx4 v[218:219], off
	v_lshl_add_u64 v[218:219], s[56:57], 0, v[182:183]
	s_add_i32 m0, s58, 0x2000
	s_nop 0
	global_load_lds_dwordx4 v[218:219], off
	v_lshl_add_u64 v[218:219], s[38:39], 0, v[176:177]
	s_mov_b32 m0, s40
	s_nop 0
	global_load_lds_dwordx4 v[218:219], off
	s_mov_b32 m0, s41
	s_nop 0
	global_load_lds_dwordx4 v[220:221], off
	s_waitcnt vmcnt(8)
	s_waitcnt lgkmcnt(0)
	s_barrier
	s_setprio 1
	s_waitcnt lgkmcnt(0)
	v_mfma_f32_16x16x32_bf16 v[60:63], v[128:131], v[160:163], v[60:63]
	v_mfma_f32_16x16x32_bf16 v[56:59], v[136:139], v[160:163], v[56:59]
	v_mfma_f32_16x16x32_bf16 v[44:47], v[128:131], v[168:171], v[44:47]
	v_mfma_f32_16x16x32_bf16 v[40:43], v[136:139], v[168:171], v[40:43]
	v_mfma_f32_16x16x32_bf16 v[28:31], v[128:131], v[190:193], v[28:31]
	v_mfma_f32_16x16x32_bf16 v[24:27], v[136:139], v[190:193], v[24:27]
	v_mfma_f32_16x16x32_bf16 v[12:15], v[128:131], v[208:211], v[12:15]
	v_mfma_f32_16x16x32_bf16 v[8:11], v[136:139], v[208:211], v[8:11]
	v_mfma_f32_16x16x32_bf16 v[60:63], v[132:135], v[164:167], v[60:63]
	v_mfma_f32_16x16x32_bf16 v[56:59], v[140:143], v[164:167], v[56:59]
	v_mfma_f32_16x16x32_bf16 v[44:47], v[132:135], v[172:175], v[44:47]
	v_mfma_f32_16x16x32_bf16 v[40:43], v[140:143], v[172:175], v[40:43]
	v_mfma_f32_16x16x32_bf16 v[28:31], v[132:135], v[194:197], v[28:31]
	v_mfma_f32_16x16x32_bf16 v[24:27], v[140:143], v[194:197], v[24:27]
	v_mfma_f32_16x16x32_bf16 v[12:15], v[132:135], v[212:215], v[12:15]
	v_mfma_f32_16x16x32_bf16 v[8:11], v[140:143], v[212:215], v[8:11]
	s_setprio 0
	s_setprio 1
	v_mfma_f32_16x16x32_bf16 v[52:55], v[144:147], v[160:163], v[52:55]
	v_mfma_f32_16x16x32_bf16 v[48:51], v[152:155], v[160:163], v[48:51]
	v_mfma_f32_16x16x32_bf16 v[36:39], v[144:147], v[168:171], v[36:39]
	v_mfma_f32_16x16x32_bf16 v[32:35], v[152:155], v[168:171], v[32:35]
	v_mfma_f32_16x16x32_bf16 v[20:23], v[144:147], v[190:193], v[20:23]
	v_mfma_f32_16x16x32_bf16 v[16:19], v[152:155], v[190:193], v[16:19]
	v_mfma_f32_16x16x32_bf16 v[4:7], v[144:147], v[208:211], v[4:7]
	v_mfma_f32_16x16x32_bf16 v[0:3], v[152:155], v[208:211], v[0:3]
	v_mfma_f32_16x16x32_bf16 v[52:55], v[148:151], v[164:167], v[52:55]
	v_mfma_f32_16x16x32_bf16 v[48:51], v[156:159], v[164:167], v[48:51]
	v_mfma_f32_16x16x32_bf16 v[36:39], v[148:151], v[172:175], v[36:39]
	v_mfma_f32_16x16x32_bf16 v[32:35], v[156:159], v[172:175], v[32:35]
	v_mfma_f32_16x16x32_bf16 v[20:23], v[148:151], v[194:197], v[20:23]
	v_mfma_f32_16x16x32_bf16 v[16:19], v[156:159], v[194:197], v[16:19]
	v_mfma_f32_16x16x32_bf16 v[4:7], v[148:151], v[212:215], v[4:7]
	v_mfma_f32_16x16x32_bf16 v[0:3], v[156:159], v[212:215], v[0:3]
	s_setprio 0
	s_barrier
	s_add_i32 s56, 0, 0x18000
	s_add_i32 s57, 0, 0x1c000
	v_add_u32_e32 v140, s56, v202
	v_add_u32_e32 v156, s57, v202
	ds_read_b128 v[128:131], v140
	ds_read_b128 v[132:135], v140 offset:1024
	ds_read_b128 v[136:139], v140 offset:2048
	ds_read_b128 v[140:143], v140 offset:3072
	ds_read_b128 v[144:147], v156
	ds_read_b128 v[148:151], v156 offset:1024
	ds_read_b128 v[152:155], v156 offset:2048
	ds_read_b128 v[156:159], v156 offset:3072
	s_add_u32 s38, s38, 0x40000
	s_addc_u32 s39, s39, 0
	s_mov_b32 m0, s43
	v_lshl_add_u64 v[222:223], s[38:39], 0, v[176:177]
	ds_read_b128 v[160:163], v206 offset:32768
	ds_read_b128 v[164:167], v206 offset:33792
	ds_read_b128 v[168:171], v206 offset:34816
	ds_read_b128 v[172:175], v206 offset:35840
	ds_read_b128 v[190:193], v206 offset:36864
	ds_read_b128 v[194:197], v206 offset:37888
	ds_read_b128 v[208:211], v206 offset:38912
	ds_read_b128 v[212:215], v206 offset:39936
	global_load_lds_dwordx4 v[222:223], off
	v_lshl_add_u64 v[222:223], s[38:39], 0, v[180:181]
	s_mov_b32 m0, s45
	s_nop 0
	global_load_lds_dwordx4 v[222:223], off
	s_waitcnt vmcnt(8)
	s_waitcnt lgkmcnt(0)
	s_barrier
	s_setprio 1
	s_waitcnt lgkmcnt(0)
	v_mfma_f32_16x16x32_bf16 v[124:127], v[128:131], v[160:163], v[124:127]
	v_mfma_f32_16x16x32_bf16 v[120:123], v[136:139], v[160:163], v[120:123]
	v_mfma_f32_16x16x32_bf16 v[108:111], v[128:131], v[168:171], v[108:111]
	v_mfma_f32_16x16x32_bf16 v[104:107], v[136:139], v[168:171], v[104:107]
	v_mfma_f32_16x16x32_bf16 v[92:95], v[128:131], v[190:193], v[92:95]
	v_mfma_f32_16x16x32_bf16 v[88:91], v[136:139], v[190:193], v[88:91]
	v_mfma_f32_16x16x32_bf16 v[76:79], v[128:131], v[208:211], v[76:79]
	v_mfma_f32_16x16x32_bf16 v[72:75], v[136:139], v[208:211], v[72:75]
	v_mfma_f32_16x16x32_bf16 v[124:127], v[132:135], v[164:167], v[124:127]
	v_mfma_f32_16x16x32_bf16 v[120:123], v[140:143], v[164:167], v[120:123]
	v_mfma_f32_16x16x32_bf16 v[108:111], v[132:135], v[172:175], v[108:111]
	v_mfma_f32_16x16x32_bf16 v[104:107], v[140:143], v[172:175], v[104:107]
	v_mfma_f32_16x16x32_bf16 v[92:95], v[132:135], v[194:197], v[92:95]
	v_mfma_f32_16x16x32_bf16 v[88:91], v[140:143], v[194:197], v[88:91]
	v_mfma_f32_16x16x32_bf16 v[76:79], v[132:135], v[212:215], v[76:79]
	v_mfma_f32_16x16x32_bf16 v[72:75], v[140:143], v[212:215], v[72:75]
	s_setprio 0
	s_setprio 1
	v_mfma_f32_16x16x32_bf16 v[116:119], v[144:147], v[160:163], v[116:119]
	v_mfma_f32_16x16x32_bf16 v[112:115], v[152:155], v[160:163], v[112:115]
	v_mfma_f32_16x16x32_bf16 v[100:103], v[144:147], v[168:171], v[100:103]
	v_mfma_f32_16x16x32_bf16 v[96:99], v[152:155], v[168:171], v[96:99]
	v_mfma_f32_16x16x32_bf16 v[84:87], v[144:147], v[190:193], v[84:87]
	v_mfma_f32_16x16x32_bf16 v[80:83], v[152:155], v[190:193], v[80:83]
	v_mfma_f32_16x16x32_bf16 v[68:71], v[144:147], v[208:211], v[68:71]
	v_mfma_f32_16x16x32_bf16 v[64:67], v[152:155], v[208:211], v[64:67]
	v_mfma_f32_16x16x32_bf16 v[116:119], v[148:151], v[164:167], v[116:119]
	v_mfma_f32_16x16x32_bf16 v[112:115], v[156:159], v[164:167], v[112:115]
	v_mfma_f32_16x16x32_bf16 v[100:103], v[148:151], v[172:175], v[100:103]
	v_mfma_f32_16x16x32_bf16 v[96:99], v[156:159], v[172:175], v[96:99]
	v_mfma_f32_16x16x32_bf16 v[84:87], v[148:151], v[194:197], v[84:87]
	v_mfma_f32_16x16x32_bf16 v[80:83], v[156:159], v[194:197], v[80:83]
	v_mfma_f32_16x16x32_bf16 v[68:71], v[148:151], v[212:215], v[68:71]
	v_mfma_f32_16x16x32_bf16 v[64:67], v[156:159], v[212:215], v[64:67]
	s_setprio 0
	s_barrier
	s_add_i32 s38, s56, s33
	v_lshl_add_u64 v[198:199], v[198:199], 0, s[10:11]
	s_mov_b32 m0, s38
	ds_read_b128 v[160:163], v206 offset:49152
	ds_read_b128 v[164:167], v206 offset:50176
	ds_read_b128 v[168:171], v206 offset:51200
	ds_read_b128 v[172:175], v206 offset:52224
	ds_read_b128 v[190:193], v206 offset:53248
	ds_read_b128 v[194:197], v206 offset:54272
	ds_read_b128 v[208:211], v206 offset:55296
	ds_read_b128 v[212:215], v206 offset:56320
	global_load_lds_dwordx4 v[198:199], off
	s_add_i32 m0, s38, 0x2000
	s_add_u32 s36, s36, 0x40080
	v_lshl_add_u64 v[198:199], v[216:217], 0, s[10:11]
	s_addc_u32 s37, s37, 0
	s_add_i32 s38, s57, s33
	global_load_lds_dwordx4 v[198:199], off
	v_lshl_add_u64 v[198:199], s[36:37], 0, v[178:179]
	s_mov_b32 m0, s38
	s_nop 0
	global_load_lds_dwordx4 v[198:199], off
	v_lshl_add_u64 v[198:199], s[36:37], 0, v[182:183]
	s_add_i32 m0, s38, 0x2000
	s_nop 0
	global_load_lds_dwordx4 v[198:199], off
	v_lshl_add_u64 v[198:199], v[218:219], 0, s[10:11]
	s_mov_b32 m0, s49
	s_nop 0
	global_load_lds_dwordx4 v[198:199], off
	v_lshl_add_u64 v[198:199], v[220:221], 0, s[10:11]
	s_mov_b32 m0, s50
	s_nop 0
	global_load_lds_dwordx4 v[198:199], off
	s_waitcnt vmcnt(8)
	s_waitcnt lgkmcnt(0)
	s_barrier
	s_setprio 1
	s_waitcnt lgkmcnt(0)
	v_mfma_f32_16x16x32_bf16 v[60:63], v[128:131], v[160:163], v[60:63]
	v_mfma_f32_16x16x32_bf16 v[56:59], v[136:139], v[160:163], v[56:59]
	v_mfma_f32_16x16x32_bf16 v[44:47], v[128:131], v[168:171], v[44:47]
	v_mfma_f32_16x16x32_bf16 v[40:43], v[136:139], v[168:171], v[40:43]
	v_mfma_f32_16x16x32_bf16 v[28:31], v[128:131], v[190:193], v[28:31]
	v_mfma_f32_16x16x32_bf16 v[24:27], v[136:139], v[190:193], v[24:27]
	v_mfma_f32_16x16x32_bf16 v[12:15], v[128:131], v[208:211], v[12:15]
	v_mfma_f32_16x16x32_bf16 v[8:11], v[136:139], v[208:211], v[8:11]
	v_mfma_f32_16x16x32_bf16 v[60:63], v[132:135], v[164:167], v[60:63]
	v_mfma_f32_16x16x32_bf16 v[56:59], v[140:143], v[164:167], v[56:59]
	v_mfma_f32_16x16x32_bf16 v[44:47], v[132:135], v[172:175], v[44:47]
	v_mfma_f32_16x16x32_bf16 v[40:43], v[140:143], v[172:175], v[40:43]
	v_mfma_f32_16x16x32_bf16 v[28:31], v[132:135], v[194:197], v[28:31]
	v_mfma_f32_16x16x32_bf16 v[24:27], v[140:143], v[194:197], v[24:27]
	v_mfma_f32_16x16x32_bf16 v[12:15], v[132:135], v[212:215], v[12:15]
	v_mfma_f32_16x16x32_bf16 v[8:11], v[140:143], v[212:215], v[8:11]
	s_setprio 0
	s_setprio 1
	v_mfma_f32_16x16x32_bf16 v[52:55], v[144:147], v[160:163], v[52:55]
	v_mfma_f32_16x16x32_bf16 v[48:51], v[152:155], v[160:163], v[48:51]
	v_mfma_f32_16x16x32_bf16 v[36:39], v[144:147], v[168:171], v[36:39]
	v_mfma_f32_16x16x32_bf16 v[32:35], v[152:155], v[168:171], v[32:35]
	v_mfma_f32_16x16x32_bf16 v[20:23], v[144:147], v[190:193], v[20:23]
	v_mfma_f32_16x16x32_bf16 v[16:19], v[152:155], v[190:193], v[16:19]
	v_mfma_f32_16x16x32_bf16 v[4:7], v[144:147], v[208:211], v[4:7]
	v_mfma_f32_16x16x32_bf16 v[0:3], v[152:155], v[208:211], v[0:3]
	v_mfma_f32_16x16x32_bf16 v[52:55], v[148:151], v[164:167], v[52:55]
	v_mfma_f32_16x16x32_bf16 v[48:51], v[156:159], v[164:167], v[48:51]
	v_mfma_f32_16x16x32_bf16 v[36:39], v[148:151], v[172:175], v[36:39]
	v_mfma_f32_16x16x32_bf16 v[32:35], v[156:159], v[172:175], v[32:35]
	v_mfma_f32_16x16x32_bf16 v[20:23], v[148:151], v[194:197], v[20:23]
	v_mfma_f32_16x16x32_bf16 v[16:19], v[156:159], v[194:197], v[16:19]
	v_mfma_f32_16x16x32_bf16 v[4:7], v[148:151], v[212:215], v[4:7]
	v_mfma_f32_16x16x32_bf16 v[0:3], v[156:159], v[212:215], v[0:3]
	s_setprio 0
	s_barrier
	s_add_i32 s55, s55, 2
	s_add_u32 s34, s34, 0x100
	s_addc_u32 s35, s35, 0
	s_add_u32 s15, s15, 0x100
	s_addc_u32 s19, s19, 0
	s_cmp_gt_u32 s55, 11
	s_cbranch_scc0 .LBB0_428
	v_readlane_b32 s56, v248, 2
	v_readlane_b32 s57, v248, 3
	v_lshl_add_u32 v240, s6, 8, v201
	v_lshl_or_b32 v241, s54, 8, v203
	v_lshlrev_b32_e32 v240, 12, v240
	v_lshl_add_u32 v240, v241, 2, v240
	s_nop 1
	global_load_dwordx4 v[224:227], v240, s[56:57]
	global_load_dwordx4 v[228:231], v240, s[56:57] offset:16
	global_load_dwordx4 v[232:235], v240, s[56:57] offset:512
	global_load_dwordx4 v[236:239], v240, s[56:57] offset:528
	ds_read_b128 v[128:131], v204
	ds_read_b128 v[132:135], v204 offset:1024
	ds_read_b128 v[136:139], v204 offset:2048
	ds_read_b128 v[140:143], v204 offset:3072
	ds_read_b128 v[144:147], v205
	ds_read_b128 v[148:151], v205 offset:1024
	ds_read_b128 v[152:155], v205 offset:2048
	ds_read_b128 v[156:159], v205 offset:3072
	s_add_u32 s36, s34, 0xfffc0080
	s_addc_u32 s37, s35, -1
	s_cmp_eq_u32 s55, 12
	s_cselect_b32 s39, s29, s37
	s_cselect_b32 s38, s28, s36
	s_cselect_b32 s37, s31, s19
	s_cselect_b32 s36, s30, s15
	v_lshl_add_u64 v[198:199], s[34:35], 0, v[184:185]
	s_add_i32 m0, s40, 0xc000
	ds_read_b128 v[160:163], v206
	ds_read_b128 v[164:167], v206 offset:1024
	ds_read_b128 v[168:171], v206 offset:2048
	ds_read_b128 v[172:175], v206 offset:3072
	ds_read_b128 v[190:193], v206 offset:4096
	ds_read_b128 v[194:197], v206 offset:5120
	ds_read_b128 v[208:211], v206 offset:6144
	ds_read_b128 v[212:215], v206 offset:7168
	global_load_lds_dwordx4 v[198:199], off
	v_lshl_add_u64 v[198:199], s[34:35], 0, v[186:187]
	s_add_i32 m0, s40, 0xe000
	s_nop 0
	global_load_lds_dwordx4 v[198:199], off
	s_waitcnt vmcnt(12)
	s_waitcnt lgkmcnt(0)
	s_barrier
	s_setprio 1
	s_waitcnt lgkmcnt(0)
	v_mfma_f32_16x16x32_bf16 v[124:127], v[128:131], v[160:163], v[124:127]
	v_mfma_f32_16x16x32_bf16 v[120:123], v[136:139], v[160:163], v[120:123]
	v_mfma_f32_16x16x32_bf16 v[108:111], v[128:131], v[168:171], v[108:111]
	v_mfma_f32_16x16x32_bf16 v[104:107], v[136:139], v[168:171], v[104:107]
	v_mfma_f32_16x16x32_bf16 v[92:95], v[128:131], v[190:193], v[92:95]
	v_mfma_f32_16x16x32_bf16 v[88:91], v[136:139], v[190:193], v[88:91]
	v_mfma_f32_16x16x32_bf16 v[76:79], v[128:131], v[208:211], v[76:79]
	v_mfma_f32_16x16x32_bf16 v[72:75], v[136:139], v[208:211], v[72:75]
	v_mfma_f32_16x16x32_bf16 v[124:127], v[132:135], v[164:167], v[124:127]
	v_mfma_f32_16x16x32_bf16 v[120:123], v[140:143], v[164:167], v[120:123]
	v_mfma_f32_16x16x32_bf16 v[108:111], v[132:135], v[172:175], v[108:111]
	v_mfma_f32_16x16x32_bf16 v[104:107], v[140:143], v[172:175], v[104:107]
	v_mfma_f32_16x16x32_bf16 v[92:95], v[132:135], v[194:197], v[92:95]
	v_mfma_f32_16x16x32_bf16 v[88:91], v[140:143], v[194:197], v[88:91]
	v_mfma_f32_16x16x32_bf16 v[76:79], v[132:135], v[212:215], v[76:79]
	v_mfma_f32_16x16x32_bf16 v[72:75], v[140:143], v[212:215], v[72:75]
	s_setprio 0
	s_setprio 1
	v_mfma_f32_16x16x32_bf16 v[116:119], v[144:147], v[160:163], v[116:119]
	v_mfma_f32_16x16x32_bf16 v[112:115], v[152:155], v[160:163], v[112:115]
	v_mfma_f32_16x16x32_bf16 v[100:103], v[144:147], v[168:171], v[100:103]
	v_mfma_f32_16x16x32_bf16 v[96:99], v[152:155], v[168:171], v[96:99]
	v_mfma_f32_16x16x32_bf16 v[84:87], v[144:147], v[190:193], v[84:87]
	v_mfma_f32_16x16x32_bf16 v[80:83], v[152:155], v[190:193], v[80:83]
	v_mfma_f32_16x16x32_bf16 v[68:71], v[144:147], v[208:211], v[68:71]
	v_mfma_f32_16x16x32_bf16 v[64:67], v[152:155], v[208:211], v[64:67]
	v_mfma_f32_16x16x32_bf16 v[116:119], v[148:151], v[164:167], v[116:119]
	v_mfma_f32_16x16x32_bf16 v[112:115], v[156:159], v[164:167], v[112:115]
	v_mfma_f32_16x16x32_bf16 v[100:103], v[148:151], v[172:175], v[100:103]
	v_mfma_f32_16x16x32_bf16 v[96:99], v[156:159], v[172:175], v[96:99]
	v_mfma_f32_16x16x32_bf16 v[84:87], v[148:151], v[194:197], v[84:87]
	v_mfma_f32_16x16x32_bf16 v[80:83], v[156:159], v[194:197], v[80:83]
	v_mfma_f32_16x16x32_bf16 v[68:71], v[148:151], v[212:215], v[68:71]
	v_mfma_f32_16x16x32_bf16 v[64:67], v[156:159], v[212:215], v[64:67]
	s_setprio 0
	s_barrier
	s_add_i32 s56, s51, s33
	v_lshl_add_u64 v[198:199], s[36:37], 0, v[178:179]
	s_mov_b32 m0, s56
	ds_read_b128 v[160:163], v206 offset:16384
	ds_read_b128 v[164:167], v206 offset:17408
	ds_read_b128 v[168:171], v206 offset:18432
	ds_read_b128 v[172:175], v206 offset:19456
	ds_read_b128 v[190:193], v206 offset:20480
	ds_read_b128 v[194:197], v206 offset:21504
	ds_read_b128 v[208:211], v206 offset:22528
	ds_read_b128 v[212:215], v206 offset:23552
	global_load_lds_dwordx4 v[198:199], off
	s_add_i32 m0, s56, 0x2000
	s_add_u32 s56, s36, 0x40000
	v_lshl_add_u64 v[216:217], s[36:37], 0, v[182:183]
	s_addc_u32 s57, s37, 0
	s_add_i32 s58, s52, s33
	global_load_lds_dwordx4 v[216:217], off
	v_lshl_add_u64 v[218:219], s[56:57], 0, v[178:179]
	s_mov_b32 m0, s58
	v_lshl_add_u64 v[220:221], s[38:39], 0, v[180:181]
	global_load_lds_dwordx4 v[218:219], off
	v_lshl_add_u64 v[218:219], s[56:57], 0, v[182:183]
	s_add_i32 m0, s58, 0x2000
	s_nop 0
	global_load_lds_dwordx4 v[218:219], off
	v_lshl_add_u64 v[218:219], s[38:39], 0, v[176:177]
	s_mov_b32 m0, s40
	s_nop 0
	global_load_lds_dwordx4 v[218:219], off
	s_mov_b32 m0, s41
	s_nop 0
	global_load_lds_dwordx4 v[220:221], off
	s_waitcnt vmcnt(12)
	s_waitcnt lgkmcnt(0)
	s_barrier
	s_setprio 1
	s_waitcnt lgkmcnt(0)
	v_mfma_f32_16x16x32_bf16 v[60:63], v[128:131], v[160:163], v[60:63]
	v_mfma_f32_16x16x32_bf16 v[56:59], v[136:139], v[160:163], v[56:59]
	v_mfma_f32_16x16x32_bf16 v[44:47], v[128:131], v[168:171], v[44:47]
	v_mfma_f32_16x16x32_bf16 v[40:43], v[136:139], v[168:171], v[40:43]
	v_mfma_f32_16x16x32_bf16 v[28:31], v[128:131], v[190:193], v[28:31]
	v_mfma_f32_16x16x32_bf16 v[24:27], v[136:139], v[190:193], v[24:27]
	v_mfma_f32_16x16x32_bf16 v[12:15], v[128:131], v[208:211], v[12:15]
	v_mfma_f32_16x16x32_bf16 v[8:11], v[136:139], v[208:211], v[8:11]
	v_mfma_f32_16x16x32_bf16 v[60:63], v[132:135], v[164:167], v[60:63]
	v_mfma_f32_16x16x32_bf16 v[56:59], v[140:143], v[164:167], v[56:59]
	v_mfma_f32_16x16x32_bf16 v[44:47], v[132:135], v[172:175], v[44:47]
	v_mfma_f32_16x16x32_bf16 v[40:43], v[140:143], v[172:175], v[40:43]
	v_mfma_f32_16x16x32_bf16 v[28:31], v[132:135], v[194:197], v[28:31]
	v_mfma_f32_16x16x32_bf16 v[24:27], v[140:143], v[194:197], v[24:27]
	v_mfma_f32_16x16x32_bf16 v[12:15], v[132:135], v[212:215], v[12:15]
	v_mfma_f32_16x16x32_bf16 v[8:11], v[140:143], v[212:215], v[8:11]
	s_setprio 0
	s_setprio 1
	v_mfma_f32_16x16x32_bf16 v[52:55], v[144:147], v[160:163], v[52:55]
	v_mfma_f32_16x16x32_bf16 v[48:51], v[152:155], v[160:163], v[48:51]
	v_mfma_f32_16x16x32_bf16 v[36:39], v[144:147], v[168:171], v[36:39]
	v_mfma_f32_16x16x32_bf16 v[32:35], v[152:155], v[168:171], v[32:35]
	v_mfma_f32_16x16x32_bf16 v[20:23], v[144:147], v[190:193], v[20:23]
	v_mfma_f32_16x16x32_bf16 v[16:19], v[152:155], v[190:193], v[16:19]
	v_mfma_f32_16x16x32_bf16 v[4:7], v[144:147], v[208:211], v[4:7]
	v_mfma_f32_16x16x32_bf16 v[0:3], v[152:155], v[208:211], v[0:3]
	v_mfma_f32_16x16x32_bf16 v[52:55], v[148:151], v[164:167], v[52:55]
	v_mfma_f32_16x16x32_bf16 v[48:51], v[156:159], v[164:167], v[48:51]
	v_mfma_f32_16x16x32_bf16 v[36:39], v[148:151], v[172:175], v[36:39]
	v_mfma_f32_16x16x32_bf16 v[32:35], v[156:159], v[172:175], v[32:35]
	v_mfma_f32_16x16x32_bf16 v[20:23], v[148:151], v[194:197], v[20:23]
	v_mfma_f32_16x16x32_bf16 v[16:19], v[156:159], v[194:197], v[16:19]
	v_mfma_f32_16x16x32_bf16 v[4:7], v[148:151], v[212:215], v[4:7]
	v_mfma_f32_16x16x32_bf16 v[0:3], v[156:159], v[212:215], v[0:3]
	s_setprio 0
	s_barrier
	s_add_i32 s56, 0, 0x18000
	s_add_i32 s57, 0, 0x1c000
	v_add_u32_e32 v140, s56, v202
	v_add_u32_e32 v156, s57, v202
	ds_read_b128 v[128:131], v140
	ds_read_b128 v[132:135], v140 offset:1024
	ds_read_b128 v[136:139], v140 offset:2048
	ds_read_b128 v[140:143], v140 offset:3072
	ds_read_b128 v[144:147], v156
	ds_read_b128 v[148:151], v156 offset:1024
	ds_read_b128 v[152:155], v156 offset:2048
	ds_read_b128 v[156:159], v156 offset:3072
	s_add_u32 s38, s38, 0x40000
	s_addc_u32 s39, s39, 0
	s_mov_b32 m0, s43
	v_lshl_add_u64 v[222:223], s[38:39], 0, v[176:177]
	ds_read_b128 v[160:163], v206 offset:32768
	ds_read_b128 v[164:167], v206 offset:33792
	ds_read_b128 v[168:171], v206 offset:34816
	ds_read_b128 v[172:175], v206 offset:35840
	ds_read_b128 v[190:193], v206 offset:36864
	ds_read_b128 v[194:197], v206 offset:37888
	ds_read_b128 v[208:211], v206 offset:38912
	ds_read_b128 v[212:215], v206 offset:39936
	global_load_lds_dwordx4 v[222:223], off
	v_lshl_add_u64 v[222:223], s[38:39], 0, v[180:181]
	s_mov_b32 m0, s45
	s_nop 0
	global_load_lds_dwordx4 v[222:223], off
	s_waitcnt vmcnt(12)
	s_waitcnt lgkmcnt(0)
	s_barrier
	s_setprio 1
	s_waitcnt lgkmcnt(0)
	v_mfma_f32_16x16x32_bf16 v[124:127], v[128:131], v[160:163], v[124:127]
	v_mfma_f32_16x16x32_bf16 v[120:123], v[136:139], v[160:163], v[120:123]
	v_mfma_f32_16x16x32_bf16 v[108:111], v[128:131], v[168:171], v[108:111]
	v_mfma_f32_16x16x32_bf16 v[104:107], v[136:139], v[168:171], v[104:107]
	v_mfma_f32_16x16x32_bf16 v[92:95], v[128:131], v[190:193], v[92:95]
	v_mfma_f32_16x16x32_bf16 v[88:91], v[136:139], v[190:193], v[88:91]
	v_mfma_f32_16x16x32_bf16 v[76:79], v[128:131], v[208:211], v[76:79]
	v_mfma_f32_16x16x32_bf16 v[72:75], v[136:139], v[208:211], v[72:75]
	v_mfma_f32_16x16x32_bf16 v[124:127], v[132:135], v[164:167], v[124:127]
	v_mfma_f32_16x16x32_bf16 v[120:123], v[140:143], v[164:167], v[120:123]
	v_mfma_f32_16x16x32_bf16 v[108:111], v[132:135], v[172:175], v[108:111]
	v_mfma_f32_16x16x32_bf16 v[104:107], v[140:143], v[172:175], v[104:107]
	v_mfma_f32_16x16x32_bf16 v[92:95], v[132:135], v[194:197], v[92:95]
	v_mfma_f32_16x16x32_bf16 v[88:91], v[140:143], v[194:197], v[88:91]
	v_mfma_f32_16x16x32_bf16 v[76:79], v[132:135], v[212:215], v[76:79]
	v_mfma_f32_16x16x32_bf16 v[72:75], v[140:143], v[212:215], v[72:75]
	s_setprio 0
	s_setprio 1
	v_mfma_f32_16x16x32_bf16 v[116:119], v[144:147], v[160:163], v[116:119]
	v_mfma_f32_16x16x32_bf16 v[112:115], v[152:155], v[160:163], v[112:115]
	v_mfma_f32_16x16x32_bf16 v[100:103], v[144:147], v[168:171], v[100:103]
	v_mfma_f32_16x16x32_bf16 v[96:99], v[152:155], v[168:171], v[96:99]
	v_mfma_f32_16x16x32_bf16 v[84:87], v[144:147], v[190:193], v[84:87]
	v_mfma_f32_16x16x32_bf16 v[80:83], v[152:155], v[190:193], v[80:83]
	v_mfma_f32_16x16x32_bf16 v[68:71], v[144:147], v[208:211], v[68:71]
	v_mfma_f32_16x16x32_bf16 v[64:67], v[152:155], v[208:211], v[64:67]
	v_mfma_f32_16x16x32_bf16 v[116:119], v[148:151], v[164:167], v[116:119]
	v_mfma_f32_16x16x32_bf16 v[112:115], v[156:159], v[164:167], v[112:115]
	v_mfma_f32_16x16x32_bf16 v[100:103], v[148:151], v[172:175], v[100:103]
	v_mfma_f32_16x16x32_bf16 v[96:99], v[156:159], v[172:175], v[96:99]
	v_mfma_f32_16x16x32_bf16 v[84:87], v[148:151], v[194:197], v[84:87]
	v_mfma_f32_16x16x32_bf16 v[80:83], v[156:159], v[194:197], v[80:83]
	v_mfma_f32_16x16x32_bf16 v[68:71], v[148:151], v[212:215], v[68:71]
	v_mfma_f32_16x16x32_bf16 v[64:67], v[156:159], v[212:215], v[64:67]
	s_setprio 0
	s_barrier
	s_add_i32 s38, s56, s33
	v_lshl_add_u64 v[198:199], v[198:199], 0, s[10:11]
	s_mov_b32 m0, s38
	ds_read_b128 v[160:163], v206 offset:49152
	ds_read_b128 v[164:167], v206 offset:50176
	ds_read_b128 v[168:171], v206 offset:51200
	ds_read_b128 v[172:175], v206 offset:52224
	ds_read_b128 v[190:193], v206 offset:53248
	ds_read_b128 v[194:197], v206 offset:54272
	ds_read_b128 v[208:211], v206 offset:55296
	ds_read_b128 v[212:215], v206 offset:56320
	global_load_lds_dwordx4 v[198:199], off
	s_add_i32 m0, s38, 0x2000
	s_add_u32 s36, s36, 0x40080
	v_lshl_add_u64 v[198:199], v[216:217], 0, s[10:11]
	s_addc_u32 s37, s37, 0
	s_add_i32 s38, s57, s33
	global_load_lds_dwordx4 v[198:199], off
	v_lshl_add_u64 v[198:199], s[36:37], 0, v[178:179]
	s_mov_b32 m0, s38
	s_nop 0
	global_load_lds_dwordx4 v[198:199], off
	v_lshl_add_u64 v[198:199], s[36:37], 0, v[182:183]
	s_add_i32 m0, s38, 0x2000
	s_nop 0
	global_load_lds_dwordx4 v[198:199], off
	v_lshl_add_u64 v[198:199], v[218:219], 0, s[10:11]
	s_mov_b32 m0, s49
	s_nop 0
	global_load_lds_dwordx4 v[198:199], off
	v_lshl_add_u64 v[198:199], v[220:221], 0, s[10:11]
	s_mov_b32 m0, s50
	s_nop 0
	global_load_lds_dwordx4 v[198:199], off
	s_waitcnt vmcnt(12)
	s_waitcnt lgkmcnt(0)
	s_barrier
	s_setprio 1
	s_waitcnt lgkmcnt(0)
	v_mfma_f32_16x16x32_bf16 v[60:63], v[128:131], v[160:163], v[60:63]
	v_mfma_f32_16x16x32_bf16 v[56:59], v[136:139], v[160:163], v[56:59]
	v_mfma_f32_16x16x32_bf16 v[44:47], v[128:131], v[168:171], v[44:47]
	v_mfma_f32_16x16x32_bf16 v[40:43], v[136:139], v[168:171], v[40:43]
	v_mfma_f32_16x16x32_bf16 v[28:31], v[128:131], v[190:193], v[28:31]
	v_mfma_f32_16x16x32_bf16 v[24:27], v[136:139], v[190:193], v[24:27]
	v_mfma_f32_16x16x32_bf16 v[12:15], v[128:131], v[208:211], v[12:15]
	v_mfma_f32_16x16x32_bf16 v[8:11], v[136:139], v[208:211], v[8:11]
	v_mfma_f32_16x16x32_bf16 v[60:63], v[132:135], v[164:167], v[60:63]
	v_mfma_f32_16x16x32_bf16 v[56:59], v[140:143], v[164:167], v[56:59]
	v_mfma_f32_16x16x32_bf16 v[44:47], v[132:135], v[172:175], v[44:47]
	v_mfma_f32_16x16x32_bf16 v[40:43], v[140:143], v[172:175], v[40:43]
	v_mfma_f32_16x16x32_bf16 v[28:31], v[132:135], v[194:197], v[28:31]
	v_mfma_f32_16x16x32_bf16 v[24:27], v[140:143], v[194:197], v[24:27]
	v_mfma_f32_16x16x32_bf16 v[12:15], v[132:135], v[212:215], v[12:15]
	v_mfma_f32_16x16x32_bf16 v[8:11], v[140:143], v[212:215], v[8:11]
	s_setprio 0
	s_setprio 1
	v_mfma_f32_16x16x32_bf16 v[52:55], v[144:147], v[160:163], v[52:55]
	v_mfma_f32_16x16x32_bf16 v[48:51], v[152:155], v[160:163], v[48:51]
	v_mfma_f32_16x16x32_bf16 v[36:39], v[144:147], v[168:171], v[36:39]
	v_mfma_f32_16x16x32_bf16 v[32:35], v[152:155], v[168:171], v[32:35]
	v_mfma_f32_16x16x32_bf16 v[20:23], v[144:147], v[190:193], v[20:23]
	v_mfma_f32_16x16x32_bf16 v[16:19], v[152:155], v[190:193], v[16:19]
	v_mfma_f32_16x16x32_bf16 v[4:7], v[144:147], v[208:211], v[4:7]
	v_mfma_f32_16x16x32_bf16 v[0:3], v[152:155], v[208:211], v[0:3]
	v_mfma_f32_16x16x32_bf16 v[52:55], v[148:151], v[164:167], v[52:55]
	v_mfma_f32_16x16x32_bf16 v[48:51], v[156:159], v[164:167], v[48:51]
	v_mfma_f32_16x16x32_bf16 v[36:39], v[148:151], v[172:175], v[36:39]
	v_mfma_f32_16x16x32_bf16 v[32:35], v[156:159], v[172:175], v[32:35]
	v_mfma_f32_16x16x32_bf16 v[20:23], v[148:151], v[194:197], v[20:23]
	v_mfma_f32_16x16x32_bf16 v[16:19], v[156:159], v[194:197], v[16:19]
	v_mfma_f32_16x16x32_bf16 v[4:7], v[148:151], v[212:215], v[4:7]
	v_mfma_f32_16x16x32_bf16 v[0:3], v[156:159], v[212:215], v[0:3]
	s_setprio 0
	s_barrier
	s_add_i32 s55, s55, 2
	s_add_u32 s34, s34, 0x100
	s_addc_u32 s35, s35, 0
	s_add_u32 s15, s15, 0x100
	s_addc_u32 s19, s19, 0
	v_readlane_b32 s56, v248, 2
	v_readlane_b32 s57, v248, 3
	v_lshl_add_u32 v241, s6, 8, v201
	v_lshl_or_b32 v197, s54, 8, v203
	v_lshlrev_b32_e32 v241, 12, v241
	v_lshl_add_u32 v241, v197, 2, v241
	v_lshrrev_b32_e32 v242, 1, v241
	s_add_u32 s58, s56, 0x10000
	s_addc_u32 s59, s57, 0
	global_load_dwordx4 v[128:131], v241, s[58:59]
	global_load_dwordx4 v[132:135], v241, s[58:59] offset:16
	global_load_dwordx4 v[136:139], v241, s[58:59] offset:512
	global_load_dwordx4 v[140:143], v241, s[58:59] offset:528
	s_add_u32 s58, s56, 0x20000
	s_addc_u32 s59, s57, 0
	global_load_dwordx4 v[144:147], v241, s[58:59]
	global_load_dwordx4 v[148:151], v241, s[58:59] offset:16
	global_load_dwordx4 v[152:155], v241, s[58:59] offset:512
	global_load_dwordx4 v[156:159], v241, s[58:59] offset:528
	s_add_u32 s58, s56, 0x30000
	s_addc_u32 s59, s57, 0
	global_load_dwordx4 v[160:163], v241, s[58:59]
	global_load_dwordx4 v[164:167], v241, s[58:59] offset:16
	global_load_dwordx4 v[168:171], v241, s[58:59] offset:512
	global_load_dwordx4 v[172:175], v241, s[58:59] offset:528
	s_add_u32 s58, s56, 0x80000
	s_addc_u32 s59, s57, 0
	global_load_dwordx4 v[208:211], v241, s[58:59]
	global_load_dwordx4 v[212:215], v241, s[58:59] offset:16
	global_load_dwordx4 v[216:219], v241, s[58:59] offset:512
	global_load_dwordx4 v[220:223], v241, s[58:59] offset:528
	v_xor_b32_e32 v198, 16, v207
	v_xor_b32_e32 v199, 32, v207
	v_lshlrev_b32_e32 v198, 2, v198
	v_lshlrev_b32_e32 v199, 2, v199
	s_waitcnt vmcnt(24)
	v_pk_add_f32 v[124:125], v[124:125], v[224:225]
	v_pk_add_f32 v[126:127], v[126:127], v[226:227]
	v_pk_add_f32 v[120:121], v[120:121], v[228:229]
	v_pk_add_f32 v[122:123], v[122:123], v[230:231]
	v_pk_add_f32 v[116:117], v[116:117], v[232:233]
	v_pk_add_f32 v[118:119], v[118:119], v[234:235]
	v_pk_add_f32 v[112:113], v[112:113], v[236:237]
	v_pk_add_f32 v[114:115], v[114:115], v[238:239]
	v_pk_mul_f32 v[244:245], v[124:125], v[124:125]
	v_pk_mul_f32 v[246:247], v[126:127], v[126:127]
	v_pk_fma_f32 v[244:245], v[120:121], v[120:121], v[244:245]
	v_pk_fma_f32 v[246:247], v[122:123], v[122:123], v[246:247]
	v_pk_fma_f32 v[244:245], v[116:117], v[116:117], v[244:245]
	v_pk_fma_f32 v[246:247], v[118:119], v[118:119], v[246:247]
	v_pk_fma_f32 v[244:245], v[112:113], v[112:113], v[244:245]
	v_pk_fma_f32 v[246:247], v[114:115], v[114:115], v[246:247]
	v_pk_add_f32 v[244:245], v[244:245], v[246:247]
	s_mov_b32 s34, 0x0
	v_cvt_pk_bf16_f32 v124, v124, v125
	v_cvt_pk_bf16_f32 v125, v126, v127
	v_cvt_pk_bf16_f32 v126, v120, v121
	v_cvt_pk_bf16_f32 v127, v122, v123
	buffer_store_dwordx4 v[124:127], v242, s[20:23], s34 offen sc1
	v_cvt_pk_bf16_f32 v116, v116, v117
	v_cvt_pk_bf16_f32 v117, v118, v119
	v_cvt_pk_bf16_f32 v118, v112, v113
	v_cvt_pk_bf16_f32 v119, v114, v115
	buffer_store_dwordx4 v[116:119], v242, s[20:23], s34 offen offset:256 sc1
	v_add_f32_e32 v249, v244, v245
	s_waitcnt vmcnt(14)
	v_pk_add_f32 v[108:109], v[108:109], v[128:129]
	v_pk_add_f32 v[110:111], v[110:111], v[130:131]
	v_pk_add_f32 v[104:105], v[104:105], v[132:133]
	v_pk_add_f32 v[106:107], v[106:107], v[134:135]
	v_pk_add_f32 v[100:101], v[100:101], v[136:137]
	v_pk_add_f32 v[102:103], v[102:103], v[138:139]
	v_pk_add_f32 v[96:97], v[96:97], v[140:141]
	v_pk_add_f32 v[98:99], v[98:99], v[142:143]
	s_add_u32 s58, s56, 0x90000
	s_addc_u32 s59, s57, 0
	global_load_dwordx4 v[128:131], v241, s[58:59]
	global_load_dwordx4 v[132:135], v241, s[58:59] offset:16
	global_load_dwordx4 v[136:139], v241, s[58:59] offset:512
	global_load_dwordx4 v[140:143], v241, s[58:59] offset:528
	v_pk_mul_f32 v[244:245], v[108:109], v[108:109]
	v_pk_mul_f32 v[246:247], v[110:111], v[110:111]
	v_pk_fma_f32 v[244:245], v[104:105], v[104:105], v[244:245]
	v_pk_fma_f32 v[246:247], v[106:107], v[106:107], v[246:247]
	v_pk_fma_f32 v[244:245], v[100:101], v[100:101], v[244:245]
	v_pk_fma_f32 v[246:247], v[102:103], v[102:103], v[246:247]
	v_pk_fma_f32 v[244:245], v[96:97], v[96:97], v[244:245]
	v_pk_fma_f32 v[246:247], v[98:99], v[98:99], v[246:247]
	v_pk_add_f32 v[244:245], v[244:245], v[246:247]
	s_mov_b32 s34, 0x8000
	v_cvt_pk_bf16_f32 v108, v108, v109
	v_cvt_pk_bf16_f32 v109, v110, v111
	v_cvt_pk_bf16_f32 v110, v104, v105
	v_cvt_pk_bf16_f32 v111, v106, v107
	buffer_store_dwordx4 v[108:111], v242, s[20:23], s34 offen sc1
	v_cvt_pk_bf16_f32 v100, v100, v101
	v_cvt_pk_bf16_f32 v101, v102, v103
	v_cvt_pk_bf16_f32 v102, v96, v97
	v_cvt_pk_bf16_f32 v103, v98, v99
	buffer_store_dwordx4 v[100:103], v242, s[20:23], s34 offen offset:256 sc1
	v_add_f32_e32 v250, v244, v245
	s_waitcnt vmcnt(16)
	v_pk_add_f32 v[92:93], v[92:93], v[144:145]
	v_pk_add_f32 v[94:95], v[94:95], v[146:147]
	v_pk_add_f32 v[88:89], v[88:89], v[148:149]
	v_pk_add_f32 v[90:91], v[90:91], v[150:151]
	v_pk_add_f32 v[84:85], v[84:85], v[152:153]
	v_pk_add_f32 v[86:87], v[86:87], v[154:155]
	v_pk_add_f32 v[80:81], v[80:81], v[156:157]
	v_pk_add_f32 v[82:83], v[82:83], v[158:159]
	s_add_u32 s58, s56, 0xa0000
	s_addc_u32 s59, s57, 0
	global_load_dwordx4 v[144:147], v241, s[58:59]
	global_load_dwordx4 v[148:151], v241, s[58:59] offset:16
	global_load_dwordx4 v[152:155], v241, s[58:59] offset:512
	global_load_dwordx4 v[156:159], v241, s[58:59] offset:528
	v_pk_mul_f32 v[244:245], v[92:93], v[92:93]
	v_pk_mul_f32 v[246:247], v[94:95], v[94:95]
	v_pk_fma_f32 v[244:245], v[88:89], v[88:89], v[244:245]
	v_pk_fma_f32 v[246:247], v[90:91], v[90:91], v[246:247]
	v_pk_fma_f32 v[244:245], v[84:85], v[84:85], v[244:245]
	v_pk_fma_f32 v[246:247], v[86:87], v[86:87], v[246:247]
	v_pk_fma_f32 v[244:245], v[80:81], v[80:81], v[244:245]
	v_pk_fma_f32 v[246:247], v[82:83], v[82:83], v[246:247]
	v_pk_add_f32 v[244:245], v[244:245], v[246:247]
	s_mov_b32 s34, 0x10000
	v_cvt_pk_bf16_f32 v92, v92, v93
	v_cvt_pk_bf16_f32 v93, v94, v95
	v_cvt_pk_bf16_f32 v94, v88, v89
	v_cvt_pk_bf16_f32 v95, v90, v91
	buffer_store_dwordx4 v[92:95], v242, s[20:23], s34 offen sc1
	v_cvt_pk_bf16_f32 v84, v84, v85
	v_cvt_pk_bf16_f32 v85, v86, v87
	v_cvt_pk_bf16_f32 v86, v80, v81
	v_cvt_pk_bf16_f32 v87, v82, v83
	buffer_store_dwordx4 v[84:87], v242, s[20:23], s34 offen offset:256 sc1
	v_add_f32_e32 v251, v244, v245
	s_waitcnt vmcnt(18)
	v_pk_add_f32 v[76:77], v[76:77], v[160:161]
	v_pk_add_f32 v[78:79], v[78:79], v[162:163]
	v_pk_add_f32 v[72:73], v[72:73], v[164:165]
	v_pk_add_f32 v[74:75], v[74:75], v[166:167]
	v_pk_add_f32 v[68:69], v[68:69], v[168:169]
	v_pk_add_f32 v[70:71], v[70:71], v[170:171]
	v_pk_add_f32 v[64:65], v[64:65], v[172:173]
	v_pk_add_f32 v[66:67], v[66:67], v[174:175]
	s_add_u32 s58, s56, 0xb0000
	s_addc_u32 s59, s57, 0
	global_load_dwordx4 v[160:163], v241, s[58:59]
	global_load_dwordx4 v[164:167], v241, s[58:59] offset:16
	global_load_dwordx4 v[168:171], v241, s[58:59] offset:512
	global_load_dwordx4 v[172:175], v241, s[58:59] offset:528
	v_pk_mul_f32 v[244:245], v[76:77], v[76:77]
	v_pk_mul_f32 v[246:247], v[78:79], v[78:79]
	v_pk_fma_f32 v[244:245], v[72:73], v[72:73], v[244:245]
	v_pk_fma_f32 v[246:247], v[74:75], v[74:75], v[246:247]
	v_pk_fma_f32 v[244:245], v[68:69], v[68:69], v[244:245]
	v_pk_fma_f32 v[246:247], v[70:71], v[70:71], v[246:247]
	v_pk_fma_f32 v[244:245], v[64:65], v[64:65], v[244:245]
	v_pk_fma_f32 v[246:247], v[66:67], v[66:67], v[246:247]
	v_pk_add_f32 v[244:245], v[244:245], v[246:247]
	s_mov_b32 s34, 0x18000
	v_cvt_pk_bf16_f32 v76, v76, v77
	v_cvt_pk_bf16_f32 v77, v78, v79
	v_cvt_pk_bf16_f32 v78, v72, v73
	v_cvt_pk_bf16_f32 v79, v74, v75
	buffer_store_dwordx4 v[76:79], v242, s[20:23], s34 offen sc1
	v_cvt_pk_bf16_f32 v68, v68, v69
	v_cvt_pk_bf16_f32 v69, v70, v71
	v_cvt_pk_bf16_f32 v70, v64, v65
	v_cvt_pk_bf16_f32 v71, v66, v67
	buffer_store_dwordx4 v[68:71], v242, s[20:23], s34 offen offset:256 sc1
	v_add_f32_e32 v252, v244, v245
	s_waitcnt vmcnt(20)
	v_pk_add_f32 v[60:61], v[60:61], v[208:209]
	v_pk_add_f32 v[62:63], v[62:63], v[210:211]
	v_pk_add_f32 v[56:57], v[56:57], v[212:213]
	v_pk_add_f32 v[58:59], v[58:59], v[214:215]
	v_pk_add_f32 v[52:53], v[52:53], v[216:217]
	v_pk_add_f32 v[54:55], v[54:55], v[218:219]
	v_pk_add_f32 v[48:49], v[48:49], v[220:221]
	v_pk_add_f32 v[50:51], v[50:51], v[222:223]
	v_pk_mul_f32 v[244:245], v[60:61], v[60:61]
	v_pk_mul_f32 v[246:247], v[62:63], v[62:63]
	v_pk_fma_f32 v[244:245], v[56:57], v[56:57], v[244:245]
	v_pk_fma_f32 v[246:247], v[58:59], v[58:59], v[246:247]
	v_pk_fma_f32 v[244:245], v[52:53], v[52:53], v[244:245]
	v_pk_fma_f32 v[246:247], v[54:55], v[54:55], v[246:247]
	v_pk_fma_f32 v[244:245], v[48:49], v[48:49], v[244:245]
	v_pk_fma_f32 v[246:247], v[50:51], v[50:51], v[246:247]
	v_pk_add_f32 v[244:245], v[244:245], v[246:247]
	s_mov_b32 s34, 0x40000
	v_cvt_pk_bf16_f32 v60, v60, v61
	v_cvt_pk_bf16_f32 v61, v62, v63
	v_cvt_pk_bf16_f32 v62, v56, v57
	v_cvt_pk_bf16_f32 v63, v58, v59
	buffer_store_dwordx4 v[60:63], v242, s[20:23], s34 offen sc1
	v_cvt_pk_bf16_f32 v52, v52, v53
	v_cvt_pk_bf16_f32 v53, v54, v55
	v_cvt_pk_bf16_f32 v54, v48, v49
	v_cvt_pk_bf16_f32 v55, v50, v51
	buffer_store_dwordx4 v[52:55], v242, s[20:23], s34 offen offset:256 sc1
	v_add_f32_e32 v253, v244, v245
	s_waitcnt vmcnt(16)
	v_pk_add_f32 v[44:45], v[44:45], v[128:129]
	v_pk_add_f32 v[46:47], v[46:47], v[130:131]
	v_pk_add_f32 v[40:41], v[40:41], v[132:133]
	v_pk_add_f32 v[42:43], v[42:43], v[134:135]
	v_pk_add_f32 v[36:37], v[36:37], v[136:137]
	v_pk_add_f32 v[38:39], v[38:39], v[138:139]
	v_pk_add_f32 v[32:33], v[32:33], v[140:141]
	v_pk_add_f32 v[34:35], v[34:35], v[142:143]
	v_pk_mul_f32 v[244:245], v[44:45], v[44:45]
	v_pk_mul_f32 v[246:247], v[46:47], v[46:47]
	v_pk_fma_f32 v[244:245], v[40:41], v[40:41], v[244:245]
	v_pk_fma_f32 v[246:247], v[42:43], v[42:43], v[246:247]
	v_pk_fma_f32 v[244:245], v[36:37], v[36:37], v[244:245]
	v_pk_fma_f32 v[246:247], v[38:39], v[38:39], v[246:247]
	v_pk_fma_f32 v[244:245], v[32:33], v[32:33], v[244:245]
	v_pk_fma_f32 v[246:247], v[34:35], v[34:35], v[246:247]
	v_pk_add_f32 v[244:245], v[244:245], v[246:247]
	s_mov_b32 s34, 0x48000
	v_cvt_pk_bf16_f32 v44, v44, v45
	v_cvt_pk_bf16_f32 v45, v46, v47
	v_cvt_pk_bf16_f32 v46, v40, v41
	v_cvt_pk_bf16_f32 v47, v42, v43
	buffer_store_dwordx4 v[44:47], v242, s[20:23], s34 offen sc1
	v_cvt_pk_bf16_f32 v36, v36, v37
	v_cvt_pk_bf16_f32 v37, v38, v39
	v_cvt_pk_bf16_f32 v38, v32, v33
	v_cvt_pk_bf16_f32 v39, v34, v35
	buffer_store_dwordx4 v[36:39], v242, s[20:23], s34 offen offset:256 sc1
	v_add_f32_e32 v254, v244, v245
	s_waitcnt vmcnt(12)
	v_pk_add_f32 v[28:29], v[28:29], v[144:145]
	v_pk_add_f32 v[30:31], v[30:31], v[146:147]
	v_pk_add_f32 v[24:25], v[24:25], v[148:149]
	v_pk_add_f32 v[26:27], v[26:27], v[150:151]
	v_pk_add_f32 v[20:21], v[20:21], v[152:153]
	v_pk_add_f32 v[22:23], v[22:23], v[154:155]
	v_pk_add_f32 v[16:17], v[16:17], v[156:157]
	v_pk_add_f32 v[18:19], v[18:19], v[158:159]
	v_pk_mul_f32 v[244:245], v[28:29], v[28:29]
	v_pk_mul_f32 v[246:247], v[30:31], v[30:31]
	v_pk_fma_f32 v[244:245], v[24:25], v[24:25], v[244:245]
	v_pk_fma_f32 v[246:247], v[26:27], v[26:27], v[246:247]
	v_pk_fma_f32 v[244:245], v[20:21], v[20:21], v[244:245]
	v_pk_fma_f32 v[246:247], v[22:23], v[22:23], v[246:247]
	v_pk_fma_f32 v[244:245], v[16:17], v[16:17], v[244:245]
	v_pk_fma_f32 v[246:247], v[18:19], v[18:19], v[246:247]
	v_pk_add_f32 v[244:245], v[244:245], v[246:247]
	s_mov_b32 s34, 0x50000
	v_cvt_pk_bf16_f32 v28, v28, v29
	v_cvt_pk_bf16_f32 v29, v30, v31
	v_cvt_pk_bf16_f32 v30, v24, v25
	v_cvt_pk_bf16_f32 v31, v26, v27
	v_cvt_pk_bf16_f32 v20, v20, v21
	v_cvt_pk_bf16_f32 v21, v22, v23
	v_cvt_pk_bf16_f32 v22, v16, v17
	v_cvt_pk_bf16_f32 v23, v18, v19
	v_add_f32_e32 v255, v244, v245
	s_waitcnt vmcnt(6)
	v_pk_add_f32 v[12:13], v[12:13], v[160:161]
	v_pk_add_f32 v[14:15], v[14:15], v[162:163]
	v_pk_add_f32 v[8:9], v[8:9], v[164:165]
	v_pk_add_f32 v[10:11], v[10:11], v[166:167]
	v_pk_add_f32 v[4:5], v[4:5], v[168:169]
	v_pk_add_f32 v[6:7], v[6:7], v[170:171]
	v_pk_add_f32 v[0:1], v[0:1], v[172:173]
	v_pk_add_f32 v[2:3], v[2:3], v[174:175]
	v_pk_mul_f32 v[244:245], v[12:13], v[12:13]
	v_pk_mul_f32 v[246:247], v[14:15], v[14:15]
	v_pk_fma_f32 v[244:245], v[8:9], v[8:9], v[244:245]
	v_pk_fma_f32 v[246:247], v[10:11], v[10:11], v[246:247]
	v_pk_fma_f32 v[244:245], v[4:5], v[4:5], v[244:245]
	v_pk_fma_f32 v[246:247], v[6:7], v[6:7], v[246:247]
	v_pk_fma_f32 v[244:245], v[0:1], v[0:1], v[244:245]
	v_pk_fma_f32 v[246:247], v[2:3], v[2:3], v[246:247]
	v_pk_add_f32 v[244:245], v[244:245], v[246:247]
	s_mov_b32 s34, 0x58000
	v_cvt_pk_bf16_f32 v12, v12, v13
	v_cvt_pk_bf16_f32 v13, v14, v15
	v_cvt_pk_bf16_f32 v14, v8, v9
	v_cvt_pk_bf16_f32 v15, v10, v11
	v_cvt_pk_bf16_f32 v4, v4, v5
	v_cvt_pk_bf16_f32 v5, v6, v7
	v_cvt_pk_bf16_f32 v6, v0, v1
	v_cvt_pk_bf16_f32 v7, v2, v3
	v_add_f32_e32 v243, v244, v245
	ds_bpermute_b32 v128, v198, v249
	ds_bpermute_b32 v129, v198, v250
	ds_bpermute_b32 v130, v198, v251
	ds_bpermute_b32 v131, v198, v252
	ds_bpermute_b32 v132, v198, v253
	ds_bpermute_b32 v133, v198, v254
	ds_bpermute_b32 v134, v198, v255
	ds_bpermute_b32 v135, v198, v243
	s_waitcnt lgkmcnt(7)
	v_add_f32_e32 v249, v249, v128
	s_waitcnt lgkmcnt(6)
	v_add_f32_e32 v250, v250, v129
	s_waitcnt lgkmcnt(5)
	v_add_f32_e32 v251, v251, v130
	s_waitcnt lgkmcnt(4)
	v_add_f32_e32 v252, v252, v131
	s_waitcnt lgkmcnt(3)
	v_add_f32_e32 v253, v253, v132
	s_waitcnt lgkmcnt(2)
	v_add_f32_e32 v254, v254, v133
	s_waitcnt lgkmcnt(1)
	v_add_f32_e32 v255, v255, v134
	s_waitcnt lgkmcnt(0)
	v_add_f32_e32 v243, v243, v135
	ds_bpermute_b32 v128, v199, v249
	ds_bpermute_b32 v129, v199, v250
	ds_bpermute_b32 v130, v199, v251
	ds_bpermute_b32 v131, v199, v252
	ds_bpermute_b32 v132, v199, v253
	ds_bpermute_b32 v133, v199, v254
	ds_bpermute_b32 v134, v199, v255
	ds_bpermute_b32 v135, v199, v243
	s_waitcnt lgkmcnt(7)
	v_add_f32_e32 v249, v249, v128
	s_waitcnt lgkmcnt(6)
	v_add_f32_e32 v250, v250, v129
	s_waitcnt lgkmcnt(5)
	v_add_f32_e32 v251, v251, v130
	s_waitcnt lgkmcnt(4)
	v_add_f32_e32 v252, v252, v131
	s_waitcnt lgkmcnt(3)
	v_add_f32_e32 v253, v253, v132
	s_waitcnt lgkmcnt(2)
	v_add_f32_e32 v254, v254, v133
	s_waitcnt lgkmcnt(1)
	v_add_f32_e32 v255, v255, v134
	s_waitcnt lgkmcnt(0)
	v_add_f32_e32 v243, v243, v135
	v_lshrrev_b32_e32 v197, 4, v207
	v_cmp_eq_u32_e64 s[58:59], 1, v197
	v_cmp_eq_u32_e64 s[60:61], 2, v197
	v_cmp_eq_u32_e32 vcc, 3, v197
	v_lshl_add_u32 v136, s6, 8, v201
	v_lshl_add_u32 v136, v197, 4, v136
	v_cndmask_b32_e64 v128, v249, v250, s[58:59]
	v_cndmask_b32_e64 v128, v128, v251, s[60:61]
	v_cndmask_b32_e32 v128, v128, v252, vcc
	v_cndmask_b32_e64 v129, v253, v254, s[58:59]
	v_cndmask_b32_e64 v129, v129, v255, s[60:61]
	v_cndmask_b32_e32 v129, v129, v243, vcc
	s_lshl_b32 s34, s54, 4
	s_lshl_b32 s35, s48, 2
	s_add_i32 s34, s34, s35
	v_lshl_add_u32 v136, v136, 6, s34
	global_store_dword v136, v128, s[26:27]
	v_add_u32_e32 v137, 0x2000, v136
	global_store_dword v137, v129, s[26:27]
	s_mov_b32 s34, 0x50000
	buffer_store_dwordx4 v[28:31], v242, s[20:23], s34 offen sc1
	s_mov_b32 s34, 0x50000
	buffer_store_dwordx4 v[20:23], v242, s[20:23], s34 offen offset:256 sc1
	s_mov_b32 s34, 0x58000
	buffer_store_dwordx4 v[12:15], v242, s[20:23], s34 offen sc1
	s_mov_b32 s34, 0x58000
	buffer_store_dwordx4 v[4:7], v242, s[20:23], s34 offen offset:256 sc1
	s_mov_b64 s[36:37], exec
	s_branch .LBB0_420
